# combo34: combo23 + barrier poll interval lengthened (s_sleep 8 instead of s_sleep 1 between polls of the arrival counter) to cut polling pressure on the counter's line
# speedup vs baseline: 1.0076x; 1.0069x over previous
; __device__ __forceinline__ unsigned xb_ld(unsigned* p)              { return __hip_atomic_load(p, __ATOMIC_RELAXED, __HIP_MEMORY_SCOPE_AGENT); }
; __device__ __forceinline__ unsigned xb_add(unsigned* p, unsigned v) { return __hip_atomic_fetch_add(p, v, __ATOMIC_RELAXED, __HIP_MEMORY_SCOPE_AGENT); }
; #define XB_SPIN(cond, bar) do { unsigned _sp = 0; while (cond) { __builtin_amdgcn_s_sleep(1); \
;     if ((++_sp & 255u) == 0u) { if (xb_ld(&(bar)[XB_TMO])) break; if (_sp > XB_SPIN_CAP) { atomicAdd(&(bar)[XB_TMO], 1u); break; } } } } while (0)
; __device__ __forceinline__ void xcd_barrier(const XcdBarrier& b) {
;     ...
;         const unsigned old = xb_add(&bar[XB_XSUB(bx)], 1u);
;         const unsigned gen = old / nloc;
;         if (old + 1u == (gen + 1u) * nloc) {
;             __builtin_amdgcn_fence(__ATOMIC_RELEASE, "agent");
;             asm volatile("s_waitcnt vmcnt(0)" ::: "memory");
;             const unsigned og = xb_add(&bar[XB_TOP], 1u);
;             const unsigned tg = og / nx;
;             if (og + 1u == (tg + 1u) * nx) xb_add(&bar[XB_TOPGEN], 1u);
;             else XB_SPIN(xb_ld(&bar[XB_TOPGEN]) == tg, bar);
;             __builtin_amdgcn_fence(__ATOMIC_ACQUIRE, "agent");
;             xb_add(&bar[XB_XGEN(bx)], 1u);
;             asm volatile("s_waitcnt vmcnt(0)" ::: "memory");
;         } else {
;             XB_SPIN(xb_ld(&bar[XB_XGEN(bx)]) == gen, bar);
;             __builtin_amdgcn_fence(__ATOMIC_ACQUIRE, "agent");
;             asm volatile("s_waitcnt vmcnt(0)" ::: "memory");
.Lxbg_spin:
	global_load_dword v16, v18, s[16:17] sc1
	s_waitcnt vmcnt(0)
	v_readfirstlane_b32 s12, v16
	s_cmp_ge_u32 s12, s20
	s_cbranch_scc1 .Lxbg_go
	s_sleep 8
	s_add_i32 s21, s21, 1
	s_cmp_lt_u32 s21, 0x40000
	s_cbranch_scc1 .Lxbg_spin

; __device__ __forceinline__ unsigned xb_ld(unsigned* p)              { return __hip_atomic_load(p, __ATOMIC_RELAXED, __HIP_MEMORY_SCOPE_AGENT); }
; __device__ __forceinline__ unsigned xb_add(unsigned* p, unsigned v) { return __hip_atomic_fetch_add(p, v, __ATOMIC_RELAXED, __HIP_MEMORY_SCOPE_AGENT); }
; #define XB_SPIN(cond, bar) do { unsigned _sp = 0; while (cond) { __builtin_amdgcn_s_sleep(1); \
;     if ((++_sp & 255u) == 0u) { if (xb_ld(&(bar)[XB_TMO])) break; if (_sp > XB_SPIN_CAP) { atomicAdd(&(bar)[XB_TMO], 1u); break; } } } } while (0)
; __device__ __forceinline__ void xcd_barrier(const XcdBarrier& b) {
;     ...
;         const unsigned old = xb_add(&bar[XB_XSUB(bx)], 1u);
;         const unsigned gen = old / nloc;
;         if (old + 1u == (gen + 1u) * nloc) {
;             __builtin_amdgcn_fence(__ATOMIC_RELEASE, "agent");
;             asm volatile("s_waitcnt vmcnt(0)" ::: "memory");
;             const unsigned og = xb_add(&bar[XB_TOP], 1u);
;             const unsigned tg = og / nx;
;             if (og + 1u == (tg + 1u) * nx) xb_add(&bar[XB_TOPGEN], 1u);
;             else XB_SPIN(xb_ld(&bar[XB_TOPGEN]) == tg, bar);
;             __builtin_amdgcn_fence(__ATOMIC_ACQUIRE, "agent");
;             xb_add(&bar[XB_XGEN(bx)], 1u);
;             asm volatile("s_waitcnt vmcnt(0)" ::: "memory");
;         } else {
;             XB_SPIN(xb_ld(&bar[XB_XGEN(bx)]) == gen, bar);
;             __builtin_amdgcn_fence(__ATOMIC_ACQUIRE, "agent");
;             asm volatile("s_waitcnt vmcnt(0)" ::: "memory");
.Lxbr_spin:
	global_load_dword v5, v10, s[16:17] sc1
	s_waitcnt vmcnt(0)
	v_readfirstlane_b32 s12, v5
	s_cmp_ge_u32 s12, s20
	s_cbranch_scc1 .Lxbr_go
	s_sleep 8
	s_add_i32 s21, s21, 1
	s_cmp_lt_u32 s21, 0x40000
	s_cbranch_scc1 .Lxbr_spin

; __device__ __forceinline__ unsigned xb_ld(unsigned* p)              { return __hip_atomic_load(p, __ATOMIC_RELAXED, __HIP_MEMORY_SCOPE_AGENT); }
; __device__ __forceinline__ unsigned xb_add(unsigned* p, unsigned v) { return __hip_atomic_fetch_add(p, v, __ATOMIC_RELAXED, __HIP_MEMORY_SCOPE_AGENT); }
; #define XB_SPIN(cond, bar) do { unsigned _sp = 0; while (cond) { __builtin_amdgcn_s_sleep(1); \
;     if ((++_sp & 255u) == 0u) { if (xb_ld(&(bar)[XB_TMO])) break; if (_sp > XB_SPIN_CAP) { atomicAdd(&(bar)[XB_TMO], 1u); break; } } } } while (0)
; __device__ __forceinline__ void xcd_barrier(const XcdBarrier& b) {
;     ...
;         const unsigned old = xb_add(&bar[XB_XSUB(bx)], 1u);
;         const unsigned gen = old / nloc;
;         if (old + 1u == (gen + 1u) * nloc) {
;             __builtin_amdgcn_fence(__ATOMIC_RELEASE, "agent");
;             asm volatile("s_waitcnt vmcnt(0)" ::: "memory");
;             const unsigned og = xb_add(&bar[XB_TOP], 1u);
;             const unsigned tg = og / nx;
;             if (og + 1u == (tg + 1u) * nx) xb_add(&bar[XB_TOPGEN], 1u);
;             else XB_SPIN(xb_ld(&bar[XB_TOPGEN]) == tg, bar);
;             __builtin_amdgcn_fence(__ATOMIC_ACQUIRE, "agent");
;             xb_add(&bar[XB_XGEN(bx)], 1u);
;             asm volatile("s_waitcnt vmcnt(0)" ::: "memory");
;         } else {
;             XB_SPIN(xb_ld(&bar[XB_XGEN(bx)]) == gen, bar);
;             __builtin_amdgcn_fence(__ATOMIC_ACQUIRE, "agent");
;             asm volatile("s_waitcnt vmcnt(0)" ::: "memory");
.Lxb0_spin:
	global_load_dword v5, v161, s[16:17] sc1
	s_waitcnt vmcnt(0)
	v_readfirstlane_b32 s12, v5
	s_cmp_ge_u32 s12, s2
	s_cbranch_scc1 .Lxb0_go
	s_sleep 8
	s_add_i32 s3, s3, 1
	s_cmp_lt_u32 s3, 0x40000
	s_cbranch_scc1 .Lxb0_spin
